# attn2
# speedup vs baseline: 1.0084x; 1.0029x over previous
; __device__ __forceinline__ void finishSM(f32x16& p0, f32x16& p1, float alpha, float& l_reg, bf16x8& pa0, bf16x8& pa1, bf16x8& pa2, bf16x8& pa3) {
; #pragma unroll
;   for (int r = 0; r < 16; ++r) p1[r] = __builtin_amdgcn_exp2f(p1[r]);
;   float ps = 0;
; #pragma unroll
;   for (int r = 0; r < 16; ++r) ps += p0[r];
; #pragma unroll
;   for (int r = 0; r < 16; ++r) ps += p1[r];
;   { auto rr = __builtin_amdgcn_permlane32_swap(__float_as_uint(ps), __float_as_uint(ps), false, false);
;     ps = __uint_as_float(rr[0]) + __uint_as_float(rr[1]); }
;   l_reg = l_reg * alpha + ps;
;     ...
;   PK4(p0, 0, pa0); PK4(p0, 8, pa1); PK4(p1, 0, pa2); PK4(p1, 8, pa3);
; __device__ __forceinline__ void qkt(f32x16& p0, f32x16& p1, const u16* Ks, const bf16x8* qr, int r32, int hi) {
;   p0 = f32x16{}; p1 = f32x16{};
; #pragma unroll
;   for (int d0 = 0; d0 < 8; ++d0) { int cb = (d0 * 16 + hi * 8) * 2;
;     bf16x8 b0 = *reinterpret_cast<const bf16x8*>((const char*)Ks + KSWZ(r32, cb));
;     bf16x8 b1 = *reinterpret_cast<const bf16x8*>((const char*)Ks + KSWZ(32 + r32, cb));
;     p0 = __builtin_amdgcn_mfma_f32_32x32x16_bf16(b0, qr[d0], p0, 0, 0, 0);
;     p1 = __builtin_amdgcn_mfma_f32_32x32x16_bf16(b1, qr[d0], p1, 0, 0, 0); }
; }
.LBB0_1644:
	ds_read_b128 v[64:67], v189 offset:49152
	ds_read_b128 v[68:71], v189 offset:57344
	ds_read_b128 v[206:209], v192 offset:49152
	ds_read_b128 v[210:213], v192 offset:57344
	v_add_f32_e32 v160, 0, v161
	v_add_f32_e32 v160, v175, v160
	s_waitcnt lgkmcnt(3)
	v_mfma_f32_32x32x16_bf16 v[80:95], v[64:67], v[124:127], 0
	v_add_f32_e32 v160, v162, v160
	v_add_f32_e32 v160, v201, v160
	v_add_f32_e32 v160, v174, v160
	v_add_f32_e32 v160, v204, v160
	v_add_f32_e32 v160, v163, v160
	v_add_f32_e32 v160, v173, v160
	v_add_f32_e32 v160, v164, v160
	s_waitcnt lgkmcnt(2)
	v_mfma_f32_32x32x16_bf16 v[64:79], v[68:71], v[124:127], 0
	v_add_f32_e32 v160, v171, v160
	v_add_f32_e32 v160, v165, v160
	v_add_f32_e32 v160, v172, v160
	v_exp_f32_e32 v158, v158
	v_add_f32_e32 v160, v166, v160
	v_exp_f32_e32 v159, v159
	v_add_f32_e32 v160, v169, v160
	s_waitcnt lgkmcnt(1)
	v_mfma_f32_32x32x16_bf16 v[80:95], v[206:209], v[120:123], v[80:95]
	v_exp_f32_e32 v156, v156
	v_add_f32_e32 v160, v167, v160
	v_exp_f32_e32 v157, v157
	v_add_f32_e32 v160, v170, v160
	v_exp_f32_e32 v152, v152
	v_add_f32_e32 v160, v158, v160
	v_exp_f32_e32 v153, v153
	s_waitcnt lgkmcnt(0)
	v_mfma_f32_32x32x16_bf16 v[64:79], v[210:213], v[120:123], v[64:79]
	ds_read_b128 v[206:209], v193 offset:49152
	ds_read_b128 v[210:213], v193 offset:57344
	v_add_f32_e32 v160, v159, v160
	v_exp_f32_e32 v148, v148
	v_add_f32_e32 v160, v156, v160
	v_exp_f32_e32 v149, v149
	v_add_f32_e32 v160, v157, v160
	v_exp_f32_e32 v144, v144
	s_waitcnt lgkmcnt(1)
	v_mfma_f32_32x32x16_bf16 v[80:95], v[206:209], v[116:119], v[80:95]
	v_add_f32_e32 v160, v152, v160
	v_exp_f32_e32 v145, v145
	v_add_f32_e32 v160, v153, v160
	v_exp_f32_e32 v154, v154
	v_add_f32_e32 v160, v148, v160
	v_exp_f32_e32 v155, v155
	v_add_f32_e32 v160, v149, v160
	s_waitcnt lgkmcnt(0)
	v_mfma_f32_32x32x16_bf16 v[64:79], v[210:213], v[116:119], v[64:79]
	ds_read_b128 v[206:209], v190 offset:49152
	ds_read_b128 v[210:213], v190 offset:57344
	v_exp_f32_e32 v150, v150
	v_add_f32_e32 v160, v144, v160
	v_exp_f32_e32 v151, v151
	v_add_f32_e32 v160, v145, v160
	v_exp_f32_e32 v146, v146
	v_add_f32_e32 v160, v154, v160
	s_waitcnt lgkmcnt(1)
	v_mfma_f32_32x32x16_bf16 v[80:95], v[206:209], v[112:115], v[80:95]
	v_exp_f32_e32 v147, v147
	v_add_f32_e32 v160, v155, v160
	v_add_f32_e32 v160, v150, v160
	v_add_f32_e32 v160, v151, v160
	v_add_f32_e32 v160, v146, v160
	v_add_f32_e32 v198, v147, v160
	v_mov_b32_e32 v199, v198
	s_waitcnt lgkmcnt(0)
	v_mfma_f32_32x32x16_bf16 v[64:79], v[210:213], v[112:115], v[64:79]
	ds_read_b128 v[206:209], v191 offset:49152
	ds_read_b128 v[210:213], v191 offset:57344
	v_permlane32_swap_b32_e32 v198, v199
	s_waitcnt lgkmcnt(1)
	v_mfma_f32_32x32x16_bf16 v[80:95], v[206:209], v[108:111], v[80:95]
	s_waitcnt lgkmcnt(0)
	v_mfma_f32_32x32x16_bf16 v[64:79], v[210:213], v[108:111], v[64:79]
	ds_read_b128 v[206:209], v194 offset:49152
	ds_read_b128 v[210:213], v194 offset:57344
	s_waitcnt lgkmcnt(1)
	v_mfma_f32_32x32x16_bf16 v[80:95], v[206:209], v[104:107], v[80:95]
	s_waitcnt lgkmcnt(0)
	v_mfma_f32_32x32x16_bf16 v[64:79], v[210:213], v[104:107], v[64:79]
	ds_read_b128 v[206:209], v195 offset:49152
	ds_read_b128 v[210:213], v195 offset:57344
	s_waitcnt lgkmcnt(1)
	v_mfma_f32_32x32x16_bf16 v[80:95], v[206:209], v[100:103], v[80:95]
	s_waitcnt lgkmcnt(0)
	v_mfma_f32_32x32x16_bf16 v[64:79], v[210:213], v[100:103], v[64:79]
	ds_read_b128 v[206:209], v196 offset:49152
	ds_read_b128 v[210:213], v196 offset:57344
	v_cvt_pk_bf16_f32 v160, v161, v175
	v_cvt_pk_bf16_f32 v161, v162, v201
	v_cvt_pk_bf16_f32 v162, v174, v204
	v_cvt_pk_bf16_f32 v163, v163, v173
	v_cvt_pk_bf16_f32 v164, v164, v171
	v_cvt_pk_bf16_f32 v165, v165, v172
	s_waitcnt lgkmcnt(1)
	v_mfma_f32_32x32x16_bf16 v[80:95], v[206:209], v[96:99], v[80:95]
	v_cvt_pk_bf16_f32 v166, v166, v169
	v_cvt_pk_bf16_f32 v167, v167, v170
	v_cvt_pk_bf16_f32 v170, v158, v159
	v_cvt_pk_bf16_f32 v171, v156, v157
	v_cvt_pk_bf16_f32 v172, v152, v153
	v_cvt_pk_bf16_f32 v173, v148, v149
	v_cvt_pk_bf16_f32 v200, v144, v145
	s_waitcnt lgkmcnt(0)
	v_mfma_f32_32x32x16_bf16 v[64:79], v[210:213], v[96:99], v[64:79]
	v_cvt_pk_bf16_f32 v201, v154, v155
	v_cvt_pk_bf16_f32 v202, v150, v151
	v_permlane32_swap_b32_e32 v160, v162
	v_cvt_pk_bf16_f32 v203, v146, v147
	v_permlane32_swap_b32_e32 v200, v202
	v_permlane32_swap_b32_e32 v161, v163
	v_permlane32_swap_b32_e32 v164, v166
	v_permlane32_swap_b32_e32 v165, v167
	v_permlane32_swap_b32_e32 v170, v172
	v_permlane32_swap_b32_e32 v171, v173
	v_permlane32_swap_b32_e32 v201, v203
	s_mov_b32 s8, 0xffff4000
	v_add_co_u32_e32 v144, vcc, s8, v178
	s_movk_i32 s8, 0x8000
	s_nop 0
	v_addc_co_u32_e32 v145, vcc, -1, v179, vcc
	v_add_co_u32_e32 v148, vcc, s8, v178
	s_mov_b32 s8, 0xfdff4000
	s_nop 0
	v_addc_co_u32_e32 v149, vcc, -1, v179, vcc
	v_add_co_u32_e32 v152, vcc, s8, v178
	s_mov_b32 s8, 0xfdff8000
	s_nop 0
	v_addc_co_u32_e32 v153, vcc, -1, v179, vcc
	v_add_co_u32_e32 v156, vcc, s8, v178
	global_load_dwordx4 v[144:147], v[144:145], off
	s_nop 0
	global_load_dwordx4 v[148:151], v[148:149], off
	v_addc_co_u32_e32 v157, vcc, -1, v179, vcc
	global_load_dwordx4 v[152:155], v[152:153], off
	s_nop 0
	global_load_dwordx4 v[156:159], v[156:157], off
	ds_read_b64_tr_b16 v[204:205], v184 offset:0
	ds_read_b64_tr_b16 v[206:207], v184 offset:0x800
	ds_read_b64_tr_b16 v[208:209], v184 offset:0x1000
	ds_read_b64_tr_b16 v[210:211], v184 offset:0x1800
	ds_read_b64_tr_b16 v[212:213], v184 offset:0x2000
	ds_read_b64_tr_b16 v[214:215], v184 offset:0x2800
	ds_read_b64_tr_b16 v[216:217], v184 offset:0x3000
	ds_read_b64_tr_b16 v[218:219], v184 offset:0x3800
	s_waitcnt lgkmcnt(0)
; #define SBAR() __builtin_amdgcn_sched_barrier(0)
; template <bool BAND>
; __device__ __forceinline__ void partialSM(f32x16& p0, f32x16& p1, float& m_reg, float& mn, float& alpha, int drel) {
;   constexpr float C = SCALE * 1.4426950408889634f;
;   if constexpr (BAND) {
; #pragma unroll
;     for (int r = 0; r < 16; ++r) {
;       int d = drel + (r & 3) + 8 * (r >> 2);
;       if ((unsigned)(d + 128) > 256u) p0[r] = -INFINITY;
;       if ((unsigned)(d + 32 + 128) > 256u) p1[r] = -INFINITY;
;     }
;   }
;   float pmax = p0[0];
; #pragma unroll
;   for (int r = 1; r < 16; ++r) pmax = fmaxf(pmax, p0[r]);
; #pragma unroll
;   for (int r = 0; r < 16; ++r) pmax = fmaxf(pmax, p1[r]);
;   { auto rr = __builtin_amdgcn_permlane32_swap(__float_as_uint(pmax), __float_as_uint(pmax), false, false);
;     pmax = fmaxf(__uint_as_float(rr[0]), __uint_as_float(rr[1])); }
;   if (__builtin_expect(__all(pmax - m_reg <= THR / SCALE), 1)) { mn = m_reg; alpha = 1.f; }
;   else { mn = fmaxf(m_reg, pmax); alpha = __builtin_amdgcn_exp2f((m_reg - mn) * C); m_reg = mn; }
;   float mnC = -mn * C;
; #pragma unroll
;   for (int r = 0; r < 16; ++r) p0[r] = fmaf(p0[r], C, mnC);
; #pragma unroll
;   for (int r = 0; r < 16; ++r) p1[r] = fmaf(p1[r], C, mnC);
; #pragma unroll
; template <int D0> __device__ __forceinline__ void pv_one(f32x16& od, int vb, bf16x8 pa0, bf16x8 pa1, bf16x8 pa2, bf16x8 pa3) {
;   const s16x4 l0 = tr_read<v_rd_off(D0, 0, 0)>(vb), h0 = tr_read<v_rd_off(D0, 0, 1)>(vb), l1 = tr_read<v_rd_off(D0, 1, 0)>(vb), h1 = tr_read<v_rd_off(D0, 1, 1)>(vb);
;   const s16x4 l2 = tr_read<v_rd_off(D0, 2, 0)>(vb), h2 = tr_read<v_rd_off(D0, 2, 1)>(vb), l3 = tr_read<v_rd_off(D0, 3, 0)>(vb), h3 = tr_read<v_rd_off(D0, 3, 1)>(vb);
;   asm volatile("s_waitcnt lgkmcnt(0)" ::: "memory"); SBAR();
;     ...
;   od = __builtin_amdgcn_mfma_f32_32x32x16_bf16(pa0, PK(l0, h0), od, 0, 0, 0);
;   od = __builtin_amdgcn_mfma_f32_32x32x16_bf16(pa1, PK(l1, h1), od, 0, 0, 0);
;   od = __builtin_amdgcn_mfma_f32_32x32x16_bf16(pa2, PK(l2, h2), od, 0, 0, 0);
;   od = __builtin_amdgcn_mfma_f32_32x32x16_bf16(pa3, PK(l3, h3), od, 0, 0, 0);
;     ...
; }
; __device__ __forceinline__ void pv_d0(f32x16* o, int vb, bf16x8 pa0, bf16x8 pa1, bf16x8 pa2, bf16x8 pa3) {
;   pv_one<0>(o[0], vb, pa0, pa1, pa2, pa3); pv_one<1>(o[1], vb, pa0, pa1, pa2, pa3); pv_one<2>(o[2], vb, pa0, pa1, pa2, pa3); pv_one<3>(o[3], vb, pa0, pa1, pa2, pa3);
	s_nop 0
	v_mfma_f32_32x32x16_bf16 v[0:15], v[160:163], v[204:207], v[0:15]
	v_max_f32_e32 v234, v81, v81
	v_max_f32_e32 v235, v80, v80
	v_max_f32_e32 v234, v235, v234
	v_max3_f32 v234, v234, v82, v83
	v_max3_f32 v234, v234, v84, v85
	v_max3_f32 v234, v234, v86, v87
	s_waitcnt vmcnt(4)
	ds_write_b128 v187, v[128:131] offset:32768
	ds_write_b128 v188, v[136:139] offset:32768
	ds_read_b64_tr_b16 v[204:205], v184 offset:0x200
	ds_read_b64_tr_b16 v[206:207], v184 offset:0xa00
	v_mfma_f32_32x32x16_bf16 v[0:15], v[164:167], v[208:211], v[0:15]
	v_max3_f32 v234, v234, v88, v89
	v_max3_f32 v234, v234, v90, v91
	v_max3_f32 v234, v234, v92, v93
	v_max3_f32 v234, v234, v94, v95
	v_max3_f32 v234, v234, v64, v65
	v_max3_f32 v234, v234, v66, v67
	ds_read_b64_tr_b16 v[208:209], v184 offset:0x1200
	ds_read_b64_tr_b16 v[210:211], v184 offset:0x1a00
	v_mfma_f32_32x32x16_bf16 v[0:15], v[170:173], v[212:215], v[0:15]
	v_max3_f32 v234, v234, v68, v69
	v_max3_f32 v234, v234, v70, v71
	v_max3_f32 v234, v234, v72, v73
	v_max3_f32 v234, v234, v74, v75
	v_max3_f32 v234, v234, v76, v77
	v_max3_f32 v234, v234, v78, v79
	ds_read_b64_tr_b16 v[212:213], v184 offset:0x2200
	ds_read_b64_tr_b16 v[214:215], v184 offset:0x2a00
	v_mfma_f32_32x32x16_bf16 v[0:15], v[200:203], v[216:219], v[0:15]
	v_mov_b32_e32 v235, v234
	s_nop 1
	v_permlane32_swap_b32_e32 v234, v235
	v_max_f32_e32 v235, v235, v235
	v_max_f32_e32 v234, v234, v234
	v_max_f32_e32 v234, v234, v235
	ds_read_b64_tr_b16 v[216:217], v184 offset:0x3200
	ds_read_b64_tr_b16 v[218:219], v184 offset:0x3a00
	s_waitcnt lgkmcnt(0)
	v_mfma_f32_32x32x16_bf16 v[48:63], v[160:163], v[204:207], v[48:63]
	v_sub_f32_e32 v235, v234, v168
	v_cmp_ge_f32_e32 vcc, s66, v235
	v_max_f32_e32 v235, v168, v168
	v_max_f32_e32 v234, v235, v234
	v_sub_f32_e32 v235, v168, v234
	v_mul_f32_e32 v235, 0x3e0293ee, v235
	ds_read_b64_tr_b16 v[204:205], v184 offset:0x400
	ds_read_b64_tr_b16 v[206:207], v184 offset:0xc00
	v_mfma_f32_32x32x16_bf16 v[48:63], v[164:167], v[208:211], v[48:63]
	v_exp_f32_e32 v235, v235
	s_cmp_eq_u64 vcc, exec
	s_cselect_b64 s[8:9], -1, 0
	s_nop 0
	v_cndmask_b32_e64 v236, v234, v168, s[8:9]
	v_mul_f32_e32 v237, 0xbe0293ee, v236
	ds_read_b64_tr_b16 v[208:209], v184 offset:0x1400
	ds_read_b64_tr_b16 v[210:211], v184 offset:0x1c00
	v_mfma_f32_32x32x16_bf16 v[48:63], v[170:173], v[212:215], v[48:63]
	ds_read_b64_tr_b16 v[212:213], v184 offset:0x2400
	ds_read_b64_tr_b16 v[214:215], v184 offset:0x2c00
	v_mfma_f32_32x32x16_bf16 v[48:63], v[200:203], v[216:219], v[48:63]
	v_fmamk_f32 v80, v80, 0x3e0293ee, v237
	v_fmamk_f32 v81, v81, 0x3e0293ee, v237
	v_fmamk_f32 v82, v82, 0x3e0293ee, v237
	v_fmamk_f32 v83, v83, 0x3e0293ee, v237
	ds_read_b64_tr_b16 v[216:217], v184 offset:0x3400
	ds_read_b64_tr_b16 v[218:219], v184 offset:0x3c00
	s_waitcnt lgkmcnt(0)
	v_mfma_f32_32x32x16_bf16 v[32:47], v[160:163], v[204:207], v[32:47]
	v_fmamk_f32 v84, v84, 0x3e0293ee, v237
	v_fmamk_f32 v85, v85, 0x3e0293ee, v237
	v_fmamk_f32 v86, v86, 0x3e0293ee, v237
	v_fmamk_f32 v87, v87, 0x3e0293ee, v237
	ds_read_b64_tr_b16 v[204:205], v184 offset:0x600
	ds_read_b64_tr_b16 v[206:207], v184 offset:0xe00
	v_mfma_f32_32x32x16_bf16 v[32:47], v[164:167], v[208:211], v[32:47]
	v_fmamk_f32 v88, v88, 0x3e0293ee, v237
	v_fmamk_f32 v89, v89, 0x3e0293ee, v237
	v_fmamk_f32 v90, v90, 0x3e0293ee, v237
	v_fmamk_f32 v91, v91, 0x3e0293ee, v237
	ds_read_b64_tr_b16 v[208:209], v184 offset:0x1600
	ds_read_b64_tr_b16 v[210:211], v184 offset:0x1e00
	v_mfma_f32_32x32x16_bf16 v[32:47], v[170:173], v[212:215], v[32:47]
	v_fmamk_f32 v92, v92, 0x3e0293ee, v237
	v_fmamk_f32 v93, v93, 0x3e0293ee, v237
	v_fmamk_f32 v94, v94, 0x3e0293ee, v237
	v_fmamk_f32 v95, v95, 0x3e0293ee, v237
	ds_read_b64_tr_b16 v[212:213], v184 offset:0x2600
	ds_read_b64_tr_b16 v[214:215], v184 offset:0x2e00
	v_mfma_f32_32x32x16_bf16 v[32:47], v[200:203], v[216:219], v[32:47]
	v_exp_f32_e32 v175, v81
	v_exp_f32_e32 v174, v83
	v_exp_f32_e32 v169, v93
	v_exp_f32_e32 v168, v95
	ds_read_b64_tr_b16 v[216:217], v184 offset:0x3600
	ds_read_b64_tr_b16 v[218:219], v184 offset:0x3e00
	s_waitcnt lgkmcnt(0)
	v_mfma_f32_32x32x16_bf16 v[16:31], v[160:163], v[204:207], v[16:31]
	v_exp_f32_e32 v160, v80
	v_exp_f32_e32 v161, v82
	v_exp_f32_e32 v162, v84
	v_exp_f32_e32 v163, v86
	v_fmamk_f32 v204, v69, 0x3e0293ee, v237
	v_fmamk_f32 v205, v70, 0x3e0293ee, v237
	v_fmamk_f32 v206, v71, 0x3e0293ee, v237
	v_fmamk_f32 v207, v72, 0x3e0293ee, v237
	v_mfma_f32_32x32x16_bf16 v[16:31], v[164:167], v[208:211], v[16:31]
	v_exp_f32_e32 v164, v88
	v_exp_f32_e32 v165, v90
	v_exp_f32_e32 v166, v92
	v_exp_f32_e32 v167, v94
	v_fmamk_f32 v208, v73, 0x3e0293ee, v237
	v_fmamk_f32 v209, v74, 0x3e0293ee, v237
	v_fmamk_f32 v210, v75, 0x3e0293ee, v237
	v_fmamk_f32 v211, v64, 0x3e0293ee, v237
	v_mfma_f32_32x32x16_bf16 v[16:31], v[170:173], v[212:215], v[16:31]
	v_exp_f32_e32 v173, v85
	v_exp_f32_e32 v172, v87
	v_exp_f32_e32 v171, v89
	v_exp_f32_e32 v170, v91
	v_fmamk_f32 v212, v65, 0x3e0293ee, v237
	v_fmamk_f32 v213, v66, 0x3e0293ee, v237
	v_fmamk_f32 v214, v67, 0x3e0293ee, v237
	v_fmamk_f32 v215, v68, 0x3e0293ee, v237
	v_mfma_f32_32x32x16_bf16 v[16:31], v[200:203], v[216:219], v[16:31]
	v_fmamk_f32 v203, v76, 0x3e0293ee, v237
	v_fmamk_f32 v216, v77, 0x3e0293ee, v237
	v_fmamk_f32 v217, v78, 0x3e0293ee, v237
	v_fmamk_f32 v202, v79, 0x3e0293ee, v237
	v_mov_b32_e32 v201, v236
	s_barrier
	s_waitcnt vmcnt(4)
	v_cndmask_b32_e64 v200, v235, 1.0, s[8:9]
	v_cmp_gt_f32_e32 vcc, 1.0, v200
	s_waitcnt vmcnt(4)
	ds_write_b128 v185, v[132:135]
	ds_write_b128 v186, v[140:143]
	s_cbranch_vccz .LBB0_1648
; __device__ __forceinline__ void finishSM(f32x16& p0, f32x16& p1, float alpha, float& l_reg, bf16x8& pa0, bf16x8& pa1, bf16x8& pa2, bf16x8& pa3) {
; #pragma unroll
;   for (int r = 0; r < 16; ++r) p1[r] = __builtin_amdgcn_exp2f(p1[r]);
;   float ps = 0;
; #pragma unroll
;   for (int r = 0; r < 16; ++r) ps += p0[r];
; #pragma unroll
;   for (int r = 0; r < 16; ++r) ps += p1[r];
;   { auto rr = __builtin_amdgcn_permlane32_swap(__float_as_uint(ps), __float_as_uint(ps), false, false);
;     ps = __uint_as_float(rr[0]) + __uint_as_float(rr[1]); }
;   l_reg = l_reg * alpha + ps;
;     ...
;   PK4(p0, 0, pa0); PK4(p0, 8, pa1); PK4(p1, 0, pa2); PK4(p1, 8, pa3);
;     ...
; }
; __device__ __forceinline__ void qkt(f32x16& p0, f32x16& p1, const u16* Ks, const bf16x8* qr, int r32, int hi) {
;   p0 = f32x16{}; p1 = f32x16{};
; #pragma unroll
;   for (int d0 = 0; d0 < 8; ++d0) { int cb = (d0 * 16 + hi * 8) * 2;
;     bf16x8 b0 = *reinterpret_cast<const bf16x8*>((const char*)Ks + KSWZ(r32, cb));
;     bf16x8 b1 = *reinterpret_cast<const bf16x8*>((const char*)Ks + KSWZ(32 + r32, cb));
;     p0 = __builtin_amdgcn_mfma_f32_32x32x16_bf16(b0, qr[d0], p0, 0, 0, 0);
;     p1 = __builtin_amdgcn_mfma_f32_32x32x16_bf16(b1, qr[d0], p1, 0, 0, 0); }
; }
	s_and_saveexec_b64 s[18:19], s[6:7]
	ds_write_b32 v182, v200 offset:128
	s_or_b64 exec, exec, s[18:19]
	s_waitcnt lgkmcnt(0)
	ds_read_b128 v[128:131], v177 offset:224
	ds_read_b128 v[132:135], v177 offset:192
	ds_read_b128 v[136:139], v177 offset:160
	ds_read_b128 v[140:143], v177 offset:128
	s_waitcnt lgkmcnt(3)
	v_pk_mul_f32 v[14:15], v[14:15], v[130:131]
	s_waitcnt lgkmcnt(2)
	v_pk_mul_f32 v[10:11], v[10:11], v[134:135]
	s_waitcnt lgkmcnt(1)
	v_pk_mul_f32 v[6:7], v[6:7], v[138:139]
	s_waitcnt lgkmcnt(0)
	v_pk_mul_f32 v[2:3], v[2:3], v[142:143]
	v_pk_mul_f32 v[12:13], v[12:13], v[128:129]
	v_pk_mul_f32 v[8:9], v[8:9], v[132:133]
	v_pk_mul_f32 v[4:5], v[4:5], v[136:137]
	v_pk_mul_f32 v[0:1], v[0:1], v[140:141]
	v_pk_mul_f32 v[62:63], v[62:63], v[130:131]
	v_pk_mul_f32 v[58:59], v[58:59], v[134:135]
	v_pk_mul_f32 v[54:55], v[54:55], v[138:139]
	v_pk_mul_f32 v[50:51], v[50:51], v[142:143]
	v_pk_mul_f32 v[60:61], v[60:61], v[128:129]
	v_pk_mul_f32 v[56:57], v[56:57], v[132:133]
	v_pk_mul_f32 v[52:53], v[52:53], v[136:137]
	v_pk_mul_f32 v[48:49], v[48:49], v[140:141]
	v_pk_mul_f32 v[46:47], v[46:47], v[130:131]
	v_pk_mul_f32 v[42:43], v[42:43], v[134:135]
	v_pk_mul_f32 v[38:39], v[38:39], v[138:139]
	v_pk_mul_f32 v[34:35], v[34:35], v[142:143]
	v_pk_mul_f32 v[44:45], v[44:45], v[128:129]
	v_pk_mul_f32 v[40:41], v[40:41], v[132:133]
	v_pk_mul_f32 v[36:37], v[36:37], v[136:137]
	v_pk_mul_f32 v[32:33], v[32:33], v[140:141]
	v_pk_mul_f32 v[30:31], v[30:31], v[130:131]
	v_pk_mul_f32 v[26:27], v[26:27], v[134:135]
	v_pk_mul_f32 v[22:23], v[22:23], v[138:139]
	v_pk_mul_f32 v[18:19], v[18:19], v[142:143]
	v_pk_mul_f32 v[28:29], v[28:29], v[128:129]
	v_pk_mul_f32 v[24:25], v[24:25], v[132:133]
	v_pk_mul_f32 v[20:21], v[20:21], v[136:137]
	v_pk_mul_f32 v[16:17], v[16:17], v[140:141]
.LBB0_1648:
	s_waitcnt lgkmcnt(0)
	s_barrier
	ds_read_b128 v[64:67], v189 offset:32768
	ds_read_b128 v[68:71], v189 offset:40960
	ds_read_b128 v[218:221], v192 offset:32768
	ds_read_b128 v[230:233], v192 offset:40960
	v_exp_f32_e32 v211, v211
	v_exp_f32_e32 v212, v212
	s_waitcnt lgkmcnt(3)
	v_mfma_f32_32x32x16_bf16 v[80:95], v[64:67], v[124:127], 0
	v_exp_f32_e32 v213, v213
	v_exp_f32_e32 v214, v214
	v_exp_f32_e32 v215, v215
	v_exp_f32_e32 v204, v204
	v_exp_f32_e32 v205, v205
	v_exp_f32_e32 v206, v206
	v_exp_f32_e32 v207, v207
	s_waitcnt lgkmcnt(2)
	v_mfma_f32_32x32x16_bf16 v[64:79], v[68:71], v[124:127], 0
	v_exp_f32_e32 v208, v208
	v_exp_f32_e32 v209, v209
	v_exp_f32_e32 v210, v210
	v_exp_f32_e32 v216, v216
	v_exp_f32_e32 v217, v217
	s_waitcnt lgkmcnt(1)
	v_mfma_f32_32x32x16_bf16 v[80:95], v[218:221], v[120:123], v[80:95]
	s_waitcnt lgkmcnt(0)
	v_mfma_f32_32x32x16_bf16 v[64:79], v[230:233], v[120:123], v[64:79]
	ds_read_b128 v[218:221], v193 offset:32768
	ds_read_b128 v[230:233], v193 offset:40960
	s_waitcnt lgkmcnt(1)
	v_mfma_f32_32x32x16_bf16 v[80:95], v[218:221], v[116:119], v[80:95]
	s_waitcnt lgkmcnt(0)
	v_mfma_f32_32x32x16_bf16 v[64:79], v[230:233], v[116:119], v[64:79]
	ds_read_b128 v[218:221], v190 offset:32768
	ds_read_b128 v[230:233], v190 offset:40960
	s_waitcnt lgkmcnt(1)
	v_mfma_f32_32x32x16_bf16 v[80:95], v[218:221], v[112:115], v[80:95]
	s_waitcnt lgkmcnt(0)
	v_mfma_f32_32x32x16_bf16 v[64:79], v[230:233], v[112:115], v[64:79]
	ds_read_b128 v[218:221], v191 offset:32768
	ds_read_b128 v[230:233], v191 offset:40960
	s_waitcnt lgkmcnt(1)
	v_mfma_f32_32x32x16_bf16 v[80:95], v[218:221], v[108:111], v[80:95]
	s_waitcnt lgkmcnt(0)
	v_mfma_f32_32x32x16_bf16 v[64:79], v[230:233], v[108:111], v[64:79]
	ds_read_b128 v[218:221], v194 offset:32768
	ds_read_b128 v[230:233], v194 offset:40960
	s_waitcnt lgkmcnt(1)
	v_mfma_f32_32x32x16_bf16 v[80:95], v[218:221], v[104:107], v[80:95]
	s_waitcnt lgkmcnt(0)
	v_mfma_f32_32x32x16_bf16 v[64:79], v[230:233], v[104:107], v[64:79]
	ds_read_b128 v[218:221], v195 offset:32768
	ds_read_b128 v[230:233], v195 offset:40960
	s_waitcnt lgkmcnt(1)
	v_mfma_f32_32x32x16_bf16 v[80:95], v[218:221], v[100:103], v[80:95]
	s_waitcnt lgkmcnt(0)
	v_mfma_f32_32x32x16_bf16 v[64:79], v[230:233], v[100:103], v[64:79]
	ds_read_b128 v[218:221], v196 offset:32768
	ds_read_b128 v[230:233], v196 offset:40960
	s_waitcnt lgkmcnt(1)
	v_mfma_f32_32x32x16_bf16 v[80:95], v[218:221], v[96:99], v[80:95]
	v_exp_f32_e32 v219, v202
	v_add_f32_e32 v202, 0, v160
	v_add_f32_e32 v202, v175, v202
	v_add_f32_e32 v202, v161, v202
	v_add_f32_e32 v202, v174, v202
	v_add_f32_e32 v202, v162, v202
	v_add_f32_e32 v202, v173, v202
	v_add_f32_e32 v202, v163, v202
	v_add_f32_e32 v202, v172, v202
	v_add_f32_e32 v202, v164, v202
	v_add_f32_e32 v202, v171, v202
	v_add_f32_e32 v202, v165, v202
	v_add_f32_e32 v202, v170, v202
	v_add_f32_e32 v202, v166, v202
	v_add_f32_e32 v202, v169, v202
	v_add_f32_e32 v202, v167, v202
	v_add_f32_e32 v202, v168, v202
	v_add_f32_e32 v202, v211, v202
	v_add_f32_e32 v202, v212, v202
	v_add_f32_e32 v202, v213, v202
	v_add_f32_e32 v202, v214, v202
	v_add_f32_e32 v202, v215, v202
	v_add_f32_e32 v202, v204, v202
	v_add_f32_e32 v202, v205, v202
	v_add_f32_e32 v202, v206, v202
	v_exp_f32_e32 v218, v203
	v_add_f32_e32 v202, v207, v202
	v_add_f32_e32 v202, v208, v202
	s_waitcnt lgkmcnt(0)
	v_mfma_f32_32x32x16_bf16 v[64:79], v[230:233], v[96:99], v[64:79]
	v_add_f32_e32 v202, v209, v202
	v_add_f32_e32 v202, v210, v202
	v_add_f32_e32 v202, v218, v202
	v_add_f32_e32 v202, v216, v202
	v_add_f32_e32 v202, v217, v202
	v_add_f32_e32 v202, v219, v202
	v_mov_b32_e32 v203, v202
	v_cvt_pk_bf16_f32 v160, v160, v175
	v_cvt_pk_bf16_f32 v161, v161, v174
	v_cvt_pk_bf16_f32 v162, v162, v173
	v_cvt_pk_bf16_f32 v163, v163, v172
	v_cvt_pk_bf16_f32 v164, v164, v171
	v_cvt_pk_bf16_f32 v165, v165, v170
	v_cvt_pk_bf16_f32 v166, v166, v169
	v_cvt_pk_bf16_f32 v167, v167, v168
	v_cvt_pk_bf16_f32 v168, v211, v212
	v_cvt_pk_bf16_f32 v169, v213, v214
	v_cvt_pk_bf16_f32 v170, v215, v204
	v_cvt_pk_bf16_f32 v171, v205, v206
	v_cvt_pk_bf16_f32 v172, v207, v208
	v_cvt_pk_bf16_f32 v173, v209, v210
	v_cvt_pk_bf16_f32 v174, v218, v216
	v_cvt_pk_bf16_f32 v175, v217, v219
	s_nop 1
	v_permlane32_swap_b32_e32 v202, v203
	v_permlane32_swap_b32_e32 v160, v162
	v_permlane32_swap_b32_e32 v161, v163
	v_permlane32_swap_b32_e32 v164, v166
	v_permlane32_swap_b32_e32 v165, v167
	v_permlane32_swap_b32_e32 v168, v170
	v_permlane32_swap_b32_e32 v169, v171
	v_permlane32_swap_b32_e32 v172, v174
	v_permlane32_swap_b32_e32 v173, v175
	s_cmp_ge_u32 s21, s23
	s_cbranch_scc1 .Lmy_d_skipld
	v_add_co_u32_e32 v128, vcc, 0xffffc000, v178
	s_nop 1
	v_addc_co_u32_e32 v129, vcc, -1, v179, vcc
	v_add_co_u32_e32 v130, vcc, 0xfdffc000, v178
	s_nop 1
	v_addc_co_u32_e32 v131, vcc, -1, v179, vcc
	v_add_co_u32_e32 v136, vcc, 0xfe000000, v178
	global_load_dwordx4 v[132:135], v[128:129], off
	s_nop 0
	global_load_dwordx4 v[128:131], v[130:131], off
	v_addc_co_u32_e32 v137, vcc, -1, v179, vcc
	global_load_dwordx4 v[140:143], v[178:179], off
	s_nop 0
	global_load_dwordx4 v[136:139], v[136:137], off
	s_waitcnt vmcnt(4)
	s_branch .Lmy_d_ldjoin

; #define SBAR() __builtin_amdgcn_sched_barrier(0)
; template <bool BAND>
; __device__ __forceinline__ void partialSM(f32x16& p0, f32x16& p1, float& m_reg, float& mn, float& alpha, int drel) {
;   constexpr float C = SCALE * 1.4426950408889634f;
;   if constexpr (BAND) {
; #pragma unroll
;     for (int r = 0; r < 16; ++r) {
;       int d = drel + (r & 3) + 8 * (r >> 2);
;       if ((unsigned)(d + 128) > 256u) p0[r] = -INFINITY;
;       if ((unsigned)(d + 32 + 128) > 256u) p1[r] = -INFINITY;
;     }
;   }
;   float pmax = p0[0];
; #pragma unroll
;   for (int r = 1; r < 16; ++r) pmax = fmaxf(pmax, p0[r]);
; #pragma unroll
;   for (int r = 0; r < 16; ++r) pmax = fmaxf(pmax, p1[r]);
;   { auto rr = __builtin_amdgcn_permlane32_swap(__float_as_uint(pmax), __float_as_uint(pmax), false, false);
;     pmax = fmaxf(__uint_as_float(rr[0]), __uint_as_float(rr[1])); }
;   if (__builtin_expect(__all(pmax - m_reg <= THR / SCALE), 1)) { mn = m_reg; alpha = 1.f; }
;   else { mn = fmaxf(m_reg, pmax); alpha = __builtin_amdgcn_exp2f((m_reg - mn) * C); m_reg = mn; }
;   float mnC = -mn * C;
; #pragma unroll
;   for (int r = 0; r < 16; ++r) p0[r] = fmaf(p0[r], C, mnC);
; #pragma unroll
;   for (int r = 0; r < 16; ++r) p1[r] = fmaf(p1[r], C, mnC);
; #pragma unroll
; template <int D0> __device__ __forceinline__ void pv_one(f32x16& od, int vb, bf16x8 pa0, bf16x8 pa1, bf16x8 pa2, bf16x8 pa3) {
;   const s16x4 l0 = tr_read<v_rd_off(D0, 0, 0)>(vb), h0 = tr_read<v_rd_off(D0, 0, 1)>(vb), l1 = tr_read<v_rd_off(D0, 1, 0)>(vb), h1 = tr_read<v_rd_off(D0, 1, 1)>(vb);
;   const s16x4 l2 = tr_read<v_rd_off(D0, 2, 0)>(vb), h2 = tr_read<v_rd_off(D0, 2, 1)>(vb), l3 = tr_read<v_rd_off(D0, 3, 0)>(vb), h3 = tr_read<v_rd_off(D0, 3, 1)>(vb);
;   asm volatile("s_waitcnt lgkmcnt(0)" ::: "memory"); SBAR();
;     ...
;   od = __builtin_amdgcn_mfma_f32_32x32x16_bf16(pa0, PK(l0, h0), od, 0, 0, 0);
;   od = __builtin_amdgcn_mfma_f32_32x32x16_bf16(pa1, PK(l1, h1), od, 0, 0, 0);
;   od = __builtin_amdgcn_mfma_f32_32x32x16_bf16(pa2, PK(l2, h2), od, 0, 0, 0);
;   od = __builtin_amdgcn_mfma_f32_32x32x16_bf16(pa3, PK(l3, h3), od, 0, 0, 0);
;     ...
; }
; __device__ __forceinline__ void pv_d0(f32x16* o, int vb, bf16x8 pa0, bf16x8 pa1, bf16x8 pa2, bf16x8 pa3) {
;   pv_one<0>(o[0], vb, pa0, pa1, pa2, pa3); pv_one<1>(o[1], vb, pa0, pa1, pa2, pa3); pv_one<2>(o[2], vb, pa0, pa1, pa2, pa3); pv_one<3>(o[3], vb, pa0, pa1, pa2, pa3);
.Lmy_d_ldjoin:
.LBB0_1650:
	ds_read_b64_tr_b16 v[204:205], v183 offset:0
	ds_read_b64_tr_b16 v[206:207], v183 offset:0x800
	ds_read_b64_tr_b16 v[208:209], v183 offset:0x1000
	ds_read_b64_tr_b16 v[210:211], v183 offset:0x1800
	ds_read_b64_tr_b16 v[212:213], v183 offset:0x2000
	ds_read_b64_tr_b16 v[214:215], v183 offset:0x2800
	ds_read_b64_tr_b16 v[216:217], v183 offset:0x3000
	ds_read_b64_tr_b16 v[218:219], v183 offset:0x3800
	s_waitcnt lgkmcnt(0)
	s_nop 0
	v_mfma_f32_32x32x16_bf16 v[0:15], v[160:163], v[204:207], v[0:15]
	v_max_f32_e32 v234, v81, v81
	v_max_f32_e32 v235, v80, v80
	v_max_f32_e32 v234, v235, v234
	v_max3_f32 v234, v234, v82, v83
	v_max3_f32 v234, v234, v84, v85
	v_max3_f32 v234, v234, v86, v87
	ds_write_b128 v187, v[152:155] offset:49152
	ds_write_b128 v188, v[156:159] offset:49152
	ds_read_b64_tr_b16 v[204:205], v183 offset:0x200
	ds_read_b64_tr_b16 v[206:207], v183 offset:0xa00
	v_mfma_f32_32x32x16_bf16 v[0:15], v[164:167], v[208:211], v[0:15]
	v_max3_f32 v234, v234, v88, v89
	v_max3_f32 v234, v234, v90, v91
	v_max3_f32 v234, v234, v92, v93
	v_max3_f32 v234, v234, v94, v95
	v_max3_f32 v234, v234, v64, v65
	v_max3_f32 v234, v234, v66, v67
	ds_read_b64_tr_b16 v[208:209], v183 offset:0x1200
	ds_read_b64_tr_b16 v[210:211], v183 offset:0x1a00
	v_mfma_f32_32x32x16_bf16 v[0:15], v[168:171], v[212:215], v[0:15]
	v_max3_f32 v234, v234, v68, v69
	v_max3_f32 v234, v234, v70, v71
	v_max3_f32 v234, v234, v72, v73
	v_max3_f32 v234, v234, v74, v75
	v_max3_f32 v234, v234, v76, v77
	v_max3_f32 v234, v234, v78, v79
	ds_read_b64_tr_b16 v[212:213], v183 offset:0x2200
	ds_read_b64_tr_b16 v[214:215], v183 offset:0x2a00
	v_mfma_f32_32x32x16_bf16 v[0:15], v[172:175], v[216:219], v[0:15]
	v_mov_b32_e32 v235, v234
	s_nop 1
	v_permlane32_swap_b32_e32 v234, v235
	v_max_f32_e32 v235, v235, v235
	v_max_f32_e32 v234, v234, v234
	v_max_f32_e32 v234, v234, v235
	ds_read_b64_tr_b16 v[216:217], v183 offset:0x3200
	ds_read_b64_tr_b16 v[218:219], v183 offset:0x3a00
	s_waitcnt lgkmcnt(0)
	v_mfma_f32_32x32x16_bf16 v[48:63], v[160:163], v[204:207], v[48:63]
	v_sub_f32_e32 v235, v234, v201
	v_cmp_ge_f32_e32 vcc, s66, v235
	v_max_f32_e32 v235, v201, v201
	v_max_f32_e32 v234, v235, v234
	v_sub_f32_e32 v235, v201, v234
	v_mul_f32_e32 v235, 0x3e0293ee, v235
	ds_read_b64_tr_b16 v[204:205], v183 offset:0x400
	ds_read_b64_tr_b16 v[206:207], v183 offset:0xc00
	v_mfma_f32_32x32x16_bf16 v[48:63], v[164:167], v[208:211], v[48:63]
	v_exp_f32_e32 v235, v235
	s_cmp_eq_u64 vcc, exec
	s_cselect_b64 s[8:9], -1, 0
	s_nop 0
	v_cndmask_b32_e64 v236, v234, v201, s[8:9]
	v_mul_f32_e32 v222, 0xbe0293ee, v236
	ds_read_b64_tr_b16 v[208:209], v183 offset:0x1400
	ds_read_b64_tr_b16 v[210:211], v183 offset:0x1c00
	v_mfma_f32_32x32x16_bf16 v[48:63], v[168:171], v[212:215], v[48:63]
	ds_read_b64_tr_b16 v[212:213], v183 offset:0x2400
	ds_read_b64_tr_b16 v[214:215], v183 offset:0x2c00
	v_mfma_f32_32x32x16_bf16 v[48:63], v[172:175], v[216:219], v[48:63]
	v_fmamk_f32 v80, v80, 0x3e0293ee, v222
	v_fmamk_f32 v81, v81, 0x3e0293ee, v222
	v_fmamk_f32 v82, v82, 0x3e0293ee, v222
	v_fmamk_f32 v83, v83, 0x3e0293ee, v222
	ds_read_b64_tr_b16 v[216:217], v183 offset:0x3400
	ds_read_b64_tr_b16 v[218:219], v183 offset:0x3c00
	s_waitcnt lgkmcnt(0)
	v_mfma_f32_32x32x16_bf16 v[32:47], v[160:163], v[204:207], v[32:47]
	v_fmamk_f32 v84, v84, 0x3e0293ee, v222
	v_fmamk_f32 v85, v85, 0x3e0293ee, v222
	v_fmamk_f32 v86, v86, 0x3e0293ee, v222
	v_fmamk_f32 v87, v87, 0x3e0293ee, v222
	ds_read_b64_tr_b16 v[204:205], v183 offset:0x600
	ds_read_b64_tr_b16 v[206:207], v183 offset:0xe00
	v_mfma_f32_32x32x16_bf16 v[32:47], v[164:167], v[208:211], v[32:47]
	v_fmamk_f32 v88, v88, 0x3e0293ee, v222
	v_fmamk_f32 v89, v89, 0x3e0293ee, v222
	v_fmamk_f32 v90, v90, 0x3e0293ee, v222
	v_fmamk_f32 v91, v91, 0x3e0293ee, v222
	ds_read_b64_tr_b16 v[208:209], v183 offset:0x1600
	ds_read_b64_tr_b16 v[210:211], v183 offset:0x1e00
	v_mfma_f32_32x32x16_bf16 v[32:47], v[168:171], v[212:215], v[32:47]
	v_fmamk_f32 v92, v92, 0x3e0293ee, v222
	v_fmamk_f32 v93, v93, 0x3e0293ee, v222
	v_fmamk_f32 v94, v94, 0x3e0293ee, v222
	v_fmamk_f32 v95, v95, 0x3e0293ee, v222
	ds_read_b64_tr_b16 v[212:213], v183 offset:0x2600
	ds_read_b64_tr_b16 v[214:215], v183 offset:0x2e00
	v_mfma_f32_32x32x16_bf16 v[32:47], v[172:175], v[216:219], v[32:47]
	v_exp_f32_e32 v201, v83
	ds_read_b64_tr_b16 v[216:217], v183 offset:0x3600
	ds_read_b64_tr_b16 v[218:219], v183 offset:0x3e00
	s_waitcnt lgkmcnt(0)
	v_mfma_f32_32x32x16_bf16 v[16:31], v[160:163], v[204:207], v[16:31]
	v_exp_f32_e32 v161, v80
	v_exp_f32_e32 v162, v82
	v_exp_f32_e32 v204, v85
	v_exp_f32_e32 v163, v86
	v_mfma_f32_32x32x16_bf16 v[16:31], v[164:167], v[208:211], v[16:31]
	v_exp_f32_e32 v164, v88
	v_exp_f32_e32 v165, v90
	v_exp_f32_e32 v166, v92
	v_exp_f32_e32 v167, v94
	v_mfma_f32_32x32x16_bf16 v[16:31], v[168:171], v[212:215], v[16:31]
	v_exp_f32_e32 v171, v89
	v_exp_f32_e32 v169, v93
	v_exp_f32_e32 v170, v95
	v_mov_b32_e32 v168, v236
	v_mfma_f32_32x32x16_bf16 v[16:31], v[172:175], v[216:219], v[16:31]
	v_exp_f32_e32 v175, v81
	v_exp_f32_e32 v174, v84
	v_exp_f32_e32 v173, v87
	v_exp_f32_e32 v172, v91
	s_barrier
; #define SBAR() __builtin_amdgcn_sched_barrier(0)
; #define SLOAD(i, k0) do { sr_[i].vs0 = *reinterpret_cast<const bf16x8*>(&Vh[(long)((k0) + sr) * LDK + sc]); sr_[i].vs1 = *reinterpret_cast<const bf16x8*>(&Vh[(long)((k0) + 32 + sr) * LDK + sc]); \
;     sr_[i].ks0 = *reinterpret_cast<const bf16x8*>(&Kh[(long)((k0) + sr) * LDK + sc]); sr_[i].ks1 = *reinterpret_cast<const bf16x8*>(&Kh[(long)((k0) + 32 + sr) * LDK + sc]); } while (0)
; template <bool BAND>
; __device__ __forceinline__ void partialSM(f32x16& p0, f32x16& p1, float& m_reg, float& mn, float& alpha, int drel) {
;     ...
;   else { mn = fmaxf(m_reg, pmax); alpha = __builtin_amdgcn_exp2f((m_reg - mn) * C); m_reg = mn; }
;   float mnC = -mn * C;
; #pragma unroll
;   for (int r = 0; r < 16; ++r) p0[r] = fmaf(p0[r], C, mnC);
; #pragma unroll
;   for (int r = 0; r < 16; ++r) p1[r] = fmaf(p1[r], C, mnC);
; #pragma unroll
;   for (int r = 0; r < 16; ++r) p0[r] = __builtin_amdgcn_exp2f(p0[r]);
; }
; __device__ __forceinline__ void finishSM(f32x16& p0, f32x16& p1, float alpha, float& l_reg, bf16x8& pa0, bf16x8& pa1, bf16x8& pa2, bf16x8& pa3) {
; #pragma unroll
;   for (int r = 0; r < 16; ++r) p1[r] = __builtin_amdgcn_exp2f(p1[r]);
;   float ps = 0;
; #pragma unroll
;   for (int r = 0; r < 16; ++r) ps += p0[r];
; #pragma unroll
;   for (int r = 0; r < 16; ++r) ps += p1[r];
;   { auto rr = __builtin_amdgcn_permlane32_swap(__float_as_uint(ps), __float_as_uint(ps), false, false);
;     ps = __uint_as_float(rr[0]) + __uint_as_float(rr[1]); }
;   l_reg = l_reg * alpha + ps;
; template <bool BAND>
; __device__ __forceinline__ void attn_body(const u16* Qb, const u16* __restrict__ Kh, const u16* __restrict__ Vh, u16* Ob, int NT, int kpos0, int qpos0, float sink_l2, char* lds, const float* __restrict__ qn) {
;     ...
;     __syncthreads(); SWAIT(); SWRITE(0, SE);
;     RESC(alB); __syncthreads();
;     SBAR(); qkt(pA0, pA1, K_lds, qr, r32, hi);
;     finishSM(pB0, pB1, alB, l_reg, pa0, pa1, pa2, pa3); SBAR();
;     if (SDEPTH == 1 || j + 3 < NT) SLOAD(SE, (j + 1 + SDEPTH) * KVBLK); SBAR();
;     pv_d0(o, vb0 + (int)SHM_V, pa0, pa1, pa2, pa3); partialSM<BAND>(pA0, pA1, m_reg, mnA, alA, dq + (j + 1) * KVBLK);
;     __syncthreads(); SWAIT(); SWRITE(1, SO);
;     RESC(alA); __syncthreads();
	s_waitcnt vmcnt(4)
	v_cndmask_b32_e64 v160, v235, 1.0, s[8:9]
	v_cmp_gt_f32_e32 vcc, 1.0, v160
	ds_write_b128 v185, v[144:147] offset:16384
	ds_write_b128 v186, v[148:151] offset:16384
	s_cbranch_vccz .LBB0_1654
	s_and_saveexec_b64 s[18:19], s[6:7]
	ds_write_b32 v182, v160 offset:128
	s_or_b64 exec, exec, s[18:19]
	s_waitcnt lgkmcnt(0)
	ds_read_b128 v[144:147], v177 offset:224
	ds_read_b128 v[148:151], v177 offset:192
	ds_read_b128 v[152:155], v177 offset:160
	ds_read_b128 v[156:159], v177 offset:128
	s_waitcnt lgkmcnt(3)
	v_pk_mul_f32 v[14:15], v[14:15], v[146:147]
	s_waitcnt lgkmcnt(2)
	v_pk_mul_f32 v[10:11], v[10:11], v[150:151]
	s_waitcnt lgkmcnt(1)
	v_pk_mul_f32 v[6:7], v[6:7], v[154:155]
	s_waitcnt lgkmcnt(0)
	v_pk_mul_f32 v[2:3], v[2:3], v[158:159]
	v_pk_mul_f32 v[12:13], v[12:13], v[144:145]
	v_pk_mul_f32 v[8:9], v[8:9], v[148:149]
	v_pk_mul_f32 v[4:5], v[4:5], v[152:153]
	v_pk_mul_f32 v[0:1], v[0:1], v[156:157]
	v_pk_mul_f32 v[62:63], v[62:63], v[146:147]
	v_pk_mul_f32 v[58:59], v[58:59], v[150:151]
	v_pk_mul_f32 v[54:55], v[54:55], v[154:155]
	v_pk_mul_f32 v[50:51], v[50:51], v[158:159]
	v_pk_mul_f32 v[60:61], v[60:61], v[144:145]
	v_pk_mul_f32 v[56:57], v[56:57], v[148:149]
	v_pk_mul_f32 v[52:53], v[52:53], v[152:153]
	v_pk_mul_f32 v[48:49], v[48:49], v[156:157]
	v_pk_mul_f32 v[46:47], v[46:47], v[146:147]
	v_pk_mul_f32 v[42:43], v[42:43], v[150:151]
	v_pk_mul_f32 v[38:39], v[38:39], v[154:155]
	v_pk_mul_f32 v[34:35], v[34:35], v[158:159]
	v_pk_mul_f32 v[44:45], v[44:45], v[144:145]
	v_pk_mul_f32 v[40:41], v[40:41], v[148:149]
	v_pk_mul_f32 v[36:37], v[36:37], v[152:153]
	v_pk_mul_f32 v[32:33], v[32:33], v[156:157]
	v_pk_mul_f32 v[30:31], v[30:31], v[146:147]
	v_pk_mul_f32 v[26:27], v[26:27], v[150:151]
	v_pk_mul_f32 v[22:23], v[22:23], v[154:155]
	v_pk_mul_f32 v[18:19], v[18:19], v[158:159]
	v_pk_mul_f32 v[28:29], v[28:29], v[144:145]
	v_pk_mul_f32 v[24:25], v[24:25], v[148:149]
	v_pk_mul_f32 v[20:21], v[20:21], v[152:153]
	v_pk_mul_f32 v[16:17], v[16:17], v[156:157]
.LBB0_1654:
	v_mul_f32_e32 v146, 0xbe0293ee, v168
	v_mov_b32_e32 v147, v146
	s_mov_b32 s8, 0x3e0293ee
	v_pk_fma_f32 v[158:159], v[64:65], s[8:9], v[146:147] op_sel_hi:[1,0,0]
	v_add_f32_e32 v64, v198, v199
	v_pk_fma_f32 v[156:157], v[66:67], s[8:9], v[146:147] op_sel_hi:[1,0,0]
	v_pk_fma_f32 v[152:153], v[68:69], s[8:9], v[146:147] op_sel_hi:[1,0,0]
	v_pk_fma_f32 v[148:149], v[70:71], s[8:9], v[146:147] op_sel_hi:[1,0,0]
	v_pk_fma_f32 v[144:145], v[72:73], s[8:9], v[146:147] op_sel_hi:[1,0,0]
	v_pk_fma_f32 v[154:155], v[74:75], s[8:9], v[146:147] op_sel_hi:[1,0,0]
	v_pk_fma_f32 v[150:151], v[76:77], s[8:9], v[146:147] op_sel_hi:[1,0,0]
	v_pk_fma_f32 v[146:147], v[78:79], s[8:9], v[146:147] op_sel_hi:[1,0,0]
	v_fmac_f32_e32 v64, v197, v180
	v_add_f32_e32 v180, v202, v203
	s_add_i32 s21, s21, 2
	s_mov_b64 s[8:9], 0x10000
	v_fmac_f32_e32 v180, v64, v200
	s_cmp_ge_u32 s21, s22
	v_lshl_add_u64 v[178:179], v[178:179], 0, s[8:9]
	s_waitcnt lgkmcnt(0)
	s_barrier
	s_cbranch_scc1 .LBB0_1656
	v_mov_b32_e32 v197, v160
	s_branch .LBB0_1644
